# k51: k50 + P1 prologue de-serialisation (first row pair's x loads issued right behind the w8 fill loads, before the fill's waits and barrier)
# speedup vs baseline: 1.0095x; 1.0095x over previous
; #define LAS __attribute__((address_space(3)))
; __global__ void __launch_bounds__(NTHR, 2) hymba_fwd(Params P) {
;     ...
;         __syncthreads();
;         LAS float* w8 = (LAS float*)lds;
; #pragma unroll
;         for (int i0 = 0; i0 < 8192; i0 += NTHR) { const int i = i0 + tid, c = i >> 10, k = i & 1023; w8[i] = P.w_in[(size_t)k * INW + NPROJ + c]; }
;         __syncthreads();
;         const int gw = blk * NWAVES + wave, NGW = G * NWAVES;
;         constexpr int NPAIR = MT / 2; const int per = (NPAIR + NGW - 1) / NGW;
;         const int p_lo = gw * per, p_hi = (p_lo + per < NPAIR) ? p_lo + per : NPAIR;
;         int cur_b = -1; f32x4 Ak[4], Bk[4]; float bsel = 0.f;
;         for (int j = 0; j < 4; ++j) { Ak[j] = (f32x4){0.f, 0.f, 0.f, 0.f}; Bk[j] = Ak[j]; }
;         f32x4 x0[4], x1[4];
;         auto rowptr = [&](int m) -> const float* { return (m < PT) ? P.x_prompt + (size_t)m * DM : P.x_sample + (size_t)(m - PT) * DM; };
;         if (p_lo < p_hi) { const float* r0 = rowptr(2 * p_lo); const float* r1 = rowptr(2 * p_lo + 1);
; #pragma unroll
;             for (int j = 0; j < 4; ++j) { x0[j] = __builtin_nontemporal_load((const f32x4*)r0 + lane + 64 * j); x1[j] = __builtin_nontemporal_load((const f32x4*)r1 + lane + 64 * j); } }
.LBB0_140:
	s_or_b64 exec, exec, s[0:1]
	v_mov_b32_e32 v2, v208
	s_waitcnt lgkmcnt(0)
	s_barrier
	v_mov_b32_e32 v1, 0
	v_and_b32_e32 v0, 0x3ff, v2
	v_mul_u32_u24_e32 v0, 0xc08, v0
	v_lshlrev_b32_e32 v0, 2, v0
	v_lshl_add_u64 v[6:7], s[60:61], 0, v[0:1]
	v_add_u32_e32 v0, 0x200, v2
	v_ashrrev_i32_e32 v8, 10, v0
	v_and_b32_e32 v0, 0x3ff, v0
	v_mul_u32_u24_e32 v0, 0xc08, v0
	v_lshlrev_b32_e32 v0, 2, v0
	v_ashrrev_i32_e32 v9, 31, v8
	v_lshl_add_u64 v[10:11], s[60:61], 0, v[0:1]
	v_add_u32_e32 v0, 0x400, v2
	v_lshl_add_u64 v[8:9], v[8:9], 2, v[10:11]
	v_ashrrev_i32_e32 v10, 10, v0
	v_add_u32_e32 v0, 0x600, v2
	v_ashrrev_i32_e32 v12, 10, v0
	v_and_b32_e32 v0, 0x3ff, v0
	v_mul_u32_u24_e32 v0, 0xc08, v0
	v_lshlrev_b32_e32 v0, 2, v0
	v_ashrrev_i32_e32 v13, 31, v12
	v_lshl_add_u64 v[14:15], s[60:61], 0, v[0:1]
	v_add_u32_e32 v0, 0x800, v2
	v_lshl_add_u64 v[12:13], v[12:13], 2, v[14:15]
	v_ashrrev_i32_e32 v14, 10, v0
	v_add_u32_e32 v0, 0xa00, v2
	v_ashrrev_i32_e32 v16, 10, v0
	v_and_b32_e32 v0, 0x3ff, v0
	v_mul_u32_u24_e32 v0, 0xc08, v0
	s_mov_b64 s[0:1], 0x3000
	v_lshlrev_b32_e32 v0, 2, v0
	v_lshl_add_u64 v[6:7], v[6:7], 0, s[0:1]
	s_movk_i32 s0, 0x3000
	v_ashrrev_i32_e32 v17, 31, v16
	v_lshl_add_u64 v[18:19], s[60:61], 0, v[0:1]
	v_add_u32_e32 v0, 0xc00, v2
	v_add_co_u32_e32 v8, vcc, s0, v8
	v_lshl_add_u64 v[16:17], v[16:17], 2, v[18:19]
	v_ashrrev_i32_e32 v18, 10, v0
	v_add_u32_e32 v0, 0xe00, v2
	v_addc_co_u32_e32 v9, vcc, 0, v9, vcc
	v_ashrrev_i32_e32 v20, 10, v0
	v_and_b32_e32 v0, 0x3ff, v0
	v_add_co_u32_e32 v12, vcc, s0, v12
	v_mul_u32_u24_e32 v0, 0xc08, v0
	s_nop 0
	v_addc_co_u32_e32 v13, vcc, 0, v13, vcc
	v_lshlrev_b32_e32 v0, 2, v0
	v_ashrrev_i32_e32 v4, 10, v2
	v_add_co_u32_e32 v16, vcc, s0, v16
	v_ashrrev_i32_e32 v21, 31, v20
	v_lshl_add_u64 v[22:23], s[60:61], 0, v[0:1]
	v_ashrrev_i32_e32 v5, 31, v4
	v_addc_co_u32_e32 v17, vcc, 0, v17, vcc
	v_lshl_add_u64 v[20:21], v[20:21], 2, v[22:23]
	v_lshl_add_u64 v[4:5], v[4:5], 2, v[6:7]
	v_ashrrev_i32_e32 v11, 31, v10
	v_ashrrev_i32_e32 v15, 31, v14
	v_ashrrev_i32_e32 v19, 31, v18
	v_add_co_u32_e32 v20, vcc, s0, v20
	v_add_u32_e32 v0, 0x1000, v2
	s_barrier
	v_lshl_add_u64 v[10:11], v[10:11], 2, v[6:7]
	v_lshl_add_u64 v[14:15], v[14:15], 2, v[6:7]
	v_lshl_add_u64 v[18:19], v[18:19], 2, v[6:7]
	v_addc_co_u32_e32 v21, vcc, 0, v21, vcc
	global_load_dword v3, v[4:5], off
	global_load_dword v22, v[8:9], off
	global_load_dword v23, v[10:11], off
	global_load_dword v24, v[12:13], off
	global_load_dword v25, v[14:15], off
	global_load_dword v26, v[16:17], off
	global_load_dword v27, v[18:19], off
	global_load_dword v28, v[20:21], off
	v_ashrrev_i32_e32 v4, 10, v0
	v_add_u32_e32 v0, 0x1200, v2
	v_ashrrev_i32_e32 v8, 10, v0
	v_and_b32_e32 v0, 0x3ff, v0
	v_mul_u32_u24_e32 v0, 0xc08, v0
	v_lshlrev_b32_e32 v0, 2, v0
	v_ashrrev_i32_e32 v9, 31, v8
	v_lshl_add_u64 v[10:11], s[60:61], 0, v[0:1]
	v_add_u32_e32 v0, 0x1400, v2
	v_lshl_add_u64 v[8:9], v[8:9], 2, v[10:11]
	v_ashrrev_i32_e32 v10, 10, v0
	v_add_u32_e32 v0, 0x1600, v2
	v_ashrrev_i32_e32 v12, 10, v0
	v_and_b32_e32 v0, 0x3ff, v0
	v_mul_u32_u24_e32 v0, 0xc08, v0
	v_lshlrev_b32_e32 v0, 2, v0
	v_ashrrev_i32_e32 v13, 31, v12
	v_lshl_add_u64 v[14:15], s[60:61], 0, v[0:1]
	v_add_u32_e32 v0, 0x1800, v2
	v_lshl_add_u64 v[12:13], v[12:13], 2, v[14:15]
	v_ashrrev_i32_e32 v14, 10, v0
	v_add_u32_e32 v0, 0x1a00, v2
	v_ashrrev_i32_e32 v16, 10, v0
	v_and_b32_e32 v0, 0x3ff, v0
	v_mul_u32_u24_e32 v0, 0xc08, v0
	v_lshlrev_b32_e32 v0, 2, v0
	v_ashrrev_i32_e32 v17, 31, v16
	v_lshl_add_u64 v[18:19], s[60:61], 0, v[0:1]
	v_add_u32_e32 v0, 0x1c00, v2
	v_lshl_add_u64 v[16:17], v[16:17], 2, v[18:19]
	v_ashrrev_i32_e32 v18, 10, v0
	v_ashrrev_i32_e32 v5, 31, v4
	v_add_co_u32_e32 v8, vcc, s0, v8
	v_ashrrev_i32_e32 v11, 31, v10
	v_ashrrev_i32_e32 v15, 31, v14
	v_ashrrev_i32_e32 v19, 31, v18
	v_add_u32_e32 v0, 0x1e00, v2
	v_lshl_add_u64 v[4:5], v[4:5], 2, v[6:7]
	v_addc_co_u32_e32 v9, vcc, 0, v9, vcc
	v_lshl_add_u64 v[10:11], v[10:11], 2, v[6:7]
	v_lshl_add_u64 v[14:15], v[14:15], 2, v[6:7]
	v_lshl_add_u64 v[6:7], v[18:19], 2, v[6:7]
	v_ashrrev_i32_e32 v18, 10, v0
	v_and_b32_e32 v0, 0x3ff, v0
	v_add_co_u32_e32 v12, vcc, s0, v12
	v_mul_u32_u24_e32 v0, 0xc08, v0
	s_nop 0
	v_addc_co_u32_e32 v13, vcc, 0, v13, vcc
	v_lshlrev_b32_e32 v0, 2, v0
	v_add_co_u32_e32 v16, vcc, s0, v16
	v_ashrrev_i32_e32 v19, 31, v18
	v_lshl_add_u64 v[20:21], s[60:61], 0, v[0:1]
	v_addc_co_u32_e32 v17, vcc, 0, v17, vcc
	v_lshl_add_u64 v[18:19], v[18:19], 2, v[20:21]
	v_add_co_u32_e32 v18, vcc, s0, v18
	s_lshl_b32 s0, s94, 3
	s_nop 0
	v_addc_co_u32_e32 v19, vcc, 0, v19, vcc
	global_load_dword v0, v[4:5], off
	s_nop 0
	global_load_dword v4, v[8:9], off
	global_load_dword v5, v[10:11], off
	s_nop 0
	global_load_dword v8, v[12:13], off
	global_load_dword v9, v[14:15], off
	global_load_dword v10, v[16:17], off
	s_nop 0
	global_load_dword v6, v[6:7], off
	s_nop 0
	global_load_dword v7, v[18:19], off
	v_readfirstlane_b32 s1, v2
	s_nop 3
	s_ashr_i32 s1, s1, 6
	s_mul_i32 s50, s2, 0x81
	s_lshl_b32 s0, s1, 4
	s_add_i32 s50, s50, s0
	s_cmp_lg_u32 s1, 0
	s_cselect_b32 s0, 1, 0
	s_add_i32 s50, s50, s0
	s_add_i32 s3, s50, 16
	s_xor_b32 s0, s0, 1
	s_add_i32 s3, s3, s0
	s_lshl_b32 s44, s50, 1
	s_add_i32 s0, s44, 0xffff0000
	s_ashr_i32 s1, s44, 31
	s_cmp_lt_i32 s50, 0x8000
	s_cselect_b32 s1, s1, 0
	s_cselect_b32 s0, s44, s0
	s_cselect_b32 s4, s37, s39
	s_cselect_b32 s5, s36, s38
	s_lshl_b64 s[0:1], s[0:1], 12
	s_add_u32 s0, s5, s0
	s_addc_u32 s1, s4, s1
	s_or_b32 s4, s44, 1
	s_add_i32 s6, s44, 0xffff0001
	s_ashr_i32 s5, s4, 31
	s_cmp_lt_i32 s4, 0x10000
	s_cselect_b32 s5, s5, 0
	s_cselect_b32 s4, s4, s6
	v_and_b32_e32 v29, 63, v2
	s_cselect_b32 s6, s37, s39
	s_cselect_b32 s7, s36, s38
	s_lshl_b64 s[4:5], s[4:5], 12
	s_add_u32 s4, s7, s4
	v_lshlrev_b32_e32 v100, 4, v29
	s_addc_u32 s5, s6, s5
	global_load_dwordx4 v[96:99], v100, s[0:1] nt
	global_load_dwordx4 v[88:91], v100, s[0:1] offset:1024 nt
	global_load_dwordx4 v[92:95], v100, s[4:5] nt
	global_load_dwordx4 v[84:87], v100, s[4:5] offset:1024 nt
	global_load_dwordx4 v[48:51], v100, s[0:1] offset:2048 nt
	global_load_dwordx4 v[40:43], v100, s[0:1] offset:3072 nt
	global_load_dwordx4 v[44:47], v100, s[4:5] offset:2048 nt
	global_load_dwordx4 v[36:39], v100, s[4:5] offset:3072 nt
	s_add_u32 s40, s92, 0x1800000
	s_addc_u32 s41, s93, 0
	v_lshl_add_u32 v11, v2, 2, 0
	s_abs_i32 s5, s0
	s_waitcnt vmcnt(22)
	ds_write2st64_b32 v11, v3, v22 offset1:8
	s_waitcnt vmcnt(20)
	ds_write2st64_b32 v11, v23, v24 offset0:16 offset1:24
	s_waitcnt vmcnt(18)
	ds_write2st64_b32 v11, v25, v26 offset0:32 offset1:40
	s_waitcnt vmcnt(16)
	ds_write2st64_b32 v11, v27, v28 offset0:48 offset1:56
	s_waitcnt vmcnt(14)
	ds_write2st64_b32 v11, v0, v4 offset0:64 offset1:72
	s_waitcnt vmcnt(12)
	ds_write2st64_b32 v11, v5, v8 offset0:80 offset1:88
	s_waitcnt vmcnt(10)
	ds_write2st64_b32 v11, v9, v10 offset0:96 offset1:104
	s_waitcnt vmcnt(8)
	ds_write2st64_b32 v11, v6, v7 offset0:112 offset1:120
	s_cmp_lt_i32 s50, s3
	v_mbcnt_lo_u32_b32 v202, -1, 0
	s_waitcnt lgkmcnt(0)
	s_barrier
; #define LAS __attribute__((address_space(3)))
; #define MOD WSP(float, WS_MOD)
; __global__ void __launch_bounds__(NTHR, 2) hymba_fwd(Params P) {
;     ...
;         int cur_b = -1; f32x4 Ak[4], Bk[4]; float bsel = 0.f;
;         for (int j = 0; j < 4; ++j) { Ak[j] = (f32x4){0.f, 0.f, 0.f, 0.f}; Bk[j] = Ak[j]; }
;         f32x4 x0[4], x1[4];
;         auto rowptr = [&](int m) -> const float* { return (m < PT) ? P.x_prompt + (size_t)m * DM : P.x_sample + (size_t)(m - PT) * DM; };
;         if (p_lo < p_hi) { const float* r0 = rowptr(2 * p_lo); const float* r1 = rowptr(2 * p_lo + 1);
; #pragma unroll
;             for (int j = 0; j < 4; ++j) { x0[j] = __builtin_nontemporal_load((const f32x4*)r0 + lane + 64 * j); x1[j] = __builtin_nontemporal_load((const f32x4*)r1 + lane + 64 * j); } }
;         for (int p = p_lo; p < p_hi; ++p) {
;             const int m0 = 2 * p;
;             const int bidx = (m0 < PT) ? (m0 >> 13) : 8 + ((m0 - PT) >> 6);
;             if (bidx != cur_b) {
;                 cur_b = bidx; const float* md = MOD + (size_t)bidx * 3072; float b2[8];
; #pragma unroll
;                 for (int c = 0; c < 8; ++c) b2[c] = 0.f;
; #pragma unroll
;                 for (int j = 0; j < 4; ++j) { const int k = 4 * lane + 256 * j;
;                     const f32x4 gv = *(const f32x4*)(P.norm_g + k), sh = *(const f32x4*)(md + k), sc = *(const f32x4*)(md + 1024 + k);
;                     Ak[j] = gv * (sc + 1.f); Bk[j] = sh;
; #pragma unroll
;                     for (int c = 0; c < 8; ++c) { const f32x4 w = *(const LAS f32x4*)(w8 + c * 1024 + k); b2[c] += (sh.x * w.x + sh.y * w.y) + (sh.z * w.z + sh.w * w.w); } }
; #pragma unroll
;                 for (int c = 0; c < 8; ++c) b2[c] = wave_sum(b2[c]);
;                 bsel = b2[0];
; #pragma unroll
;                 for (int c = 1; c < 8; ++c) bsel = (((lane >> 2) & 7) == c) ? b2[c] : bsel;
;                 bsel += P.b_f[(lane >> 2) & 7];
	s_cbranch_scc0 .LBB0_150
	v_and_b32_e32 v4, 63, v2
	v_and_b32_e32 v3, 32, v2
	v_cmp_eq_u32_e64 s[0:1], 0, v3
	v_and_b32_e32 v3, 16, v2
	v_cmp_eq_u32_e64 s[4:5], 0, v3
	v_and_b32_e32 v3, 8, v2
	v_cmp_eq_u32_e64 s[6:7], 0, v3
	v_and_b32_e32 v3, 4, v2
	v_lshlrev_b32_e32 v6, 2, v4
	v_bfe_u32 v102, v2, 2, 3
	v_cmp_eq_u32_e64 s[8:9], 0, v3
	v_lshlrev_b32_e32 v8, 3, v4
	v_mov_b32_e32 v9, v1
	v_and_b32_e32 v3, 3, v2
	v_lshlrev_b32_e32 v0, 2, v102
	v_lshl_add_u64 v[106:107], s[40:41], 0, v[8:9]
	v_cmp_eq_u32_e64 s[10:11], 0, v3
	v_bfe_u32 v103, v2, 5, 1
	v_cmp_gt_u32_e64 s[12:13], 32, v4
	v_mov_b32_e32 v101, v1
	v_or_b32_e32 v8, 0x100, v6
	v_or_b32_e32 v10, 0x200, v6
	v_or_b32_e32 v12, 0x300, v6
	v_mov_b32_e32 v2, v1
	v_mov_b32_e32 v3, v1
	v_lshlrev_b32_e32 v130, 4, v4
	v_lshl_add_u64 v[104:105], s[62:63], 0, v[0:1]
	v_lshl_add_u64 v[108:109], s[42:43], 0, v[0:1]
	v_lshl_add_u64 v[110:111], s[58:59], 0, v[100:101]
	v_mov_b32_e32 v0, v1
	v_lshlrev_b32_e32 v101, 2, v6
	v_lshlrev_b32_e32 v113, 2, v8
	v_lshlrev_b32_e32 v128, 2, v10
	v_lshlrev_b32_e32 v129, 2, v12
	v_mov_b64_e32 v[6:7], v[2:3]
	v_mov_b64_e32 v[10:11], v[2:3]
	v_mov_b64_e32 v[14:15], v[2:3]
	v_mov_b64_e32 v[26:27], v[2:3]
	v_mov_b64_e32 v[18:19], v[2:3]
	v_mov_b64_e32 v[22:23], v[2:3]
	v_mov_b64_e32 v[30:31], v[2:3]
	v_mov_b64_e32 v[34:35], v[2:3]
	v_cmp_eq_u32_e64 s[14:15], 1, v102
	v_cmp_eq_u32_e64 s[16:17], 2, v102
	v_cmp_eq_u32_e64 s[18:19], 3, v102
	v_cmp_eq_u32_e64 s[20:21], 4, v102
	v_cmp_eq_u32_e64 s[22:23], 5, v102
	v_cmp_eq_u32_e64 s[24:25], 6, v102
	v_cmp_eq_u32_e64 s[26:27], 7, v102
	s_mov_b32 s51, -1
	v_mbcnt_hi_u32_b32 v131, -1, v202
	s_mov_b32 s33, 0x800000
	v_mov_b32_e32 v132, 0x3ecc95a3
	s_mov_b32 s34, 0xffff
	s_movk_i32 s35, 0x840
	v_mov_b32_e32 v112, 0x358637bd
	v_mov_b32_e32 v133, 0x7f800000
	v_mov_b32_e32 v134, 0x7fc00000
	v_mov_b32_e32 v135, 0xff800000
	v_mov_b64_e32 v[4:5], v[0:1]
	v_mov_b64_e32 v[8:9], v[0:1]
	v_mov_b64_e32 v[12:13], v[0:1]
	v_mov_b64_e32 v[24:25], v[0:1]
	v_mov_b64_e32 v[16:17], v[0:1]
	v_mov_b64_e32 v[20:21], v[0:1]
	v_mov_b64_e32 v[28:29], v[0:1]
	v_mov_b64_e32 v[32:33], v[0:1]
	v_mov_b32_e32 v136, 0
	s_branch .LBB0_143
